# scan: the two workgroups of a (b,h) pair remapped onto the same XCD (bid%8) so the shared staged tiles hit the same L2
# speedup vs baseline: 1.0117x; 1.0117x over previous
.LBB0_154:
	s_and_b64 vcc, exec, s[0:1]
	s_cbranch_vccz .LBB0_168
	s_and_b32 s98, s80, 7
	s_lshl_b32 s98, s98, 3
	s_lshr_b32 s99, s80, 3
	s_or_b32 s80, s98, s99
	s_ashr_i32 s0, s80, 1
	s_ashr_i32 s1, s0, 31
	s_lshl_b64 s[4:5], s[0:1], 8
	s_add_u32 s4, s2, s4
	s_addc_u32 s5, s3, s5
	v_lshlrev_b32_e32 v0, 2, v160
	v_lshl_add_u64 v[2:3], s[4:5], 0, v[0:1]
	v_add_co_u32_e32 v2, vcc, 0x300000, v2
	v_readlane_b32 s4, v254, 48
	s_nop 0
	v_addc_co_u32_e32 v3, vcc, 0, v3, vcc
	flat_load_dword v37, v[2:3]
	s_cmp_gt_i32 s4, 3
	s_cselect_b64 s[4:5], -1, 0
	s_and_b64 vcc, exec, s[4:5]
	s_cbranch_vccnz .LBB0_157
	s_setprio 2
